# win-attention unit prologue: sink-logit load no longer forces its own memory round trip before the K/V tile loads (one wait for all prologue loads); on top of noflush+peel stack
# speedup vs baseline: 1.0049x; 1.0010x over previous
.LBB0_785:
	v_readfirstlane_b32 s69, v105
	s_ashr_i32 s71, s69, 6
	s_lshl_b32 s22, s71, 5
	s_and_b32 s68, s22, 32
	v_or_b32_e32 v2, s68, v111
	s_ashr_i32 s22, s69, 7
	v_lshlrev_b32_e32 v0, 12, v2
	v_lshl_add_u64 v[4:5], s[20:21], 0, v[0:1]
	s_lshl_b32 s20, s22, 6
	s_ashr_i32 s21, s20, 31
	v_lshl_add_u64 v[4:5], s[20:21], 1, v[4:5]
	v_lshlrev_b32_e32 v0, 1, v104
	s_mov_b64 s[24:25], s[0:1]
	v_lshl_add_u64 v[4:5], v[4:5], 0, v[0:1]
	global_load_dwordx4 v[80:83], v[4:5], off
	global_load_dwordx4 v[84:87], v[4:5], off offset:32
	global_load_dwordx4 v[88:91], v[4:5], off offset:64
	global_load_dwordx4 v[92:95], v[4:5], off offset:96
	s_load_dwordx2 s[24:25], s[24:25], 0x70
	s_waitcnt lgkmcnt(0)
	s_cmp_eq_u64 s[24:25], 0
	s_cselect_b64 s[20:21], -1, 0
	s_and_b64 vcc, exec, s[20:21]
	s_cbranch_vccnz .LBB0_787
	s_add_u32 s23, s24, s4
	s_addc_u32 s24, s25, s5
	s_and_b64 s[18:19], exec, s[18:19]
	s_cselect_b32 s18, 5, 2
	s_lshr_b32 s18, s34, s18
	s_lshl_b32 s18, s18, 4
	s_and_b32 s18, s18, 0x70
	s_add_u32 s25, s23, s18
	s_addc_u32 s24, s24, 0
	s_ashr_i32 s23, s22, 31
	s_lshl_b64 s[18:19], s[22:23], 2
	s_add_u32 s18, s25, s18
	s_addc_u32 s19, s24, s19
	global_load_dword v134, v1, s[18:19]
	v_mov_b32_e32 v117, v118
	s_branch .LBB0_788

.LBB0_788:
	v_lshl_add_u64 v[4:5], s[14:15], 0, v[106:107]
	global_load_dwordx4 v[96:99], v[4:5], off
	v_lshl_add_u64 v[4:5], s[16:17], 0, v[106:107]
	v_lshl_add_u64 v[8:9], s[16:17], 0, v[108:109]
	global_load_dwordx4 v[100:103], v[4:5], off
	v_add_u32_e32 v0, v122, v120
	global_load_dwordx4 v[8:11], v[8:9], off
	v_lshl_add_u64 v[4:5], s[14:15], 0, v[108:109]
	global_load_dwordx4 v[4:7], v[4:5], off
	s_cmp_lt_i32 s72, 3
	s_waitcnt vmcnt(0)
	v_mul_f32_e32 v134, 0x3fb8aa3b, v134
	ds_write_b128 v0, v[96:99]
	v_add_u32_e32 v0, v110, v120
	ds_write_b128 v0, v[100:103] offset:9216
	v_add_u32_e32 v0, v112, v120
	ds_write_b128 v0, v[4:7] offset:21504
	ds_write_b128 v133, v[8:11] offset:30720
	s_cbranch_scc1 .LBB0_790
	v_lshl_add_u64 v[4:5], s[14:15], 0, v[114:115]
	global_load_dwordx4 v[96:99], v[4:5], off
	v_lshl_add_u64 v[4:5], s[16:17], 0, v[114:115]
	global_load_dwordx4 v[100:103], v[4:5], off
